# stack on the EpiUp version: NSA branch-finish gate logits loaded together up front; mLSTM prefix sum/max scans via DPP instead of ds_bpermute; prep weight copies two items in flight with rebalanced co
# speedup vs baseline: 1.0071x; 1.0071x over previous
.LBB0_203:
	s_mov_b32 s39, s83
	v_lshl_add_u64 v[102:103], s[38:39], 2, v[148:149]
	global_load_dword v99, v[102:103], off
	global_load_dword v105, v[102:103], off offset:12
	global_load_dword v106, v[102:103], off offset:24
	global_load_dword v107, v[102:103], off offset:36
	ds_bpermute_b32 v96, v193, v154
	s_waitcnt lgkmcnt(0)
	v_add_f32_e32 v96, v154, v96
	ds_bpermute_b32 v97, v194, v96
	s_waitcnt lgkmcnt(0)
	v_add_f32_e32 v98, v96, v97
	s_waitcnt vmcnt(0) lgkmcnt(0)
	v_mul_f32_e32 v99, 0xbfb8aa3b, v99
	v_exp_f32_e32 v99, v99
	s_nop 0
	v_add_f32_e32 v99, 1.0, v99
	v_rcp_f32_e32 v99, v99
	s_nop 0
	v_div_scale_f32 v100, s[0:1], v98, v98, v99
	v_rcp_f32_e32 v101, v100
	s_mov_b64 s[0:1], -1
	v_fma_f32 v102, -v100, v101, 1.0
	v_fmac_f32_e32 v101, v102, v101
	v_div_scale_f32 v102, vcc, v99, v98, v99
	v_mul_f32_e32 v103, v102, v101
	v_fma_f32 v104, -v100, v103, v102
	v_fmac_f32_e32 v103, v104, v101
	v_fma_f32 v100, -v100, v103, v102
	v_div_fmas_f32 v100, v100, v101, v103
	v_div_fixup_f32 v98, v100, v98, v99
	v_mul_f32_e32 v93, v93, v98
	s_and_b64 vcc, exec, s[12:13]
	s_cbranch_vccz .LBB0_205
	ds_read2st64_b32 v[100:101], v192 offset1:1
	s_mov_b64 s[0:1], 0
	s_waitcnt lgkmcnt(0)
	v_add_f32_e32 v99, v93, v101
	v_fmac_f32_e32 v100, v92, v98
	ds_write2st64_b32 v192, v100, v99 offset1:1
	ds_read2st64_b32 v[100:101], v192 offset0:2 offset1:3
	s_waitcnt lgkmcnt(0)
	v_fma_f32 v99, v94, v98, v100
	v_fmac_f32_e32 v101, v95, v98
	ds_write2st64_b32 v192, v99, v101 offset0:2 offset1:3

.LBB0_214:
	v_mov_b32_e32 v80, v105
	ds_bpermute_b32 v81, v193, v156
	s_waitcnt lgkmcnt(0)
	v_add_f32_e32 v81, v156, v81
	ds_bpermute_b32 v82, v194, v81
	s_waitcnt lgkmcnt(0)
	v_add_f32_e32 v81, v81, v82
	v_mul_f32_e32 v80, 0xbfb8aa3b, v80
	v_exp_f32_e32 v80, v80
	s_nop 0
	v_add_f32_e32 v80, 1.0, v80
	v_rcp_f32_e32 v80, v80
	s_nop 0
	v_div_scale_f32 v82, s[0:1], v81, v81, v80
	v_rcp_f32_e32 v83, v82
	v_div_scale_f32 v84, vcc, v80, v81, v80
	s_mov_b64 s[0:1], -1
	v_fma_f32 v85, -v82, v83, 1.0
	v_fmac_f32_e32 v83, v85, v83
	v_mul_f32_e32 v85, v84, v83
	v_fma_f32 v86, -v82, v85, v84
	v_fmac_f32_e32 v85, v86, v83
	v_fma_f32 v82, -v82, v85, v84
	v_div_fmas_f32 v82, v82, v83, v85
	v_div_fixup_f32 v80, v82, v81, v80
	s_and_b64 vcc, exec, s[4:5]
	v_mul_f32_e32 v77, v77, v80
	s_cbranch_vccz .LBB0_245
	s_andn2_b64 vcc, exec, s[0:1]
	s_cbranch_vccz .LBB0_246

.LBB0_223:
	v_mov_b32_e32 v64, v106
	ds_bpermute_b32 v65, v193, v157
	s_waitcnt lgkmcnt(0)
	v_add_f32_e32 v65, v157, v65
	ds_bpermute_b32 v66, v194, v65
	s_waitcnt lgkmcnt(0)
	v_add_f32_e32 v65, v65, v66
	v_mul_f32_e32 v64, 0xbfb8aa3b, v64
	v_exp_f32_e32 v64, v64
	s_nop 0
	v_add_f32_e32 v64, 1.0, v64
	v_rcp_f32_e32 v64, v64
	s_nop 0
	v_div_scale_f32 v66, s[0:1], v65, v65, v64
	v_rcp_f32_e32 v67, v66
	v_div_scale_f32 v68, vcc, v64, v65, v64
	s_mov_b64 s[0:1], -1
	v_fma_f32 v69, -v66, v67, 1.0
	v_fmac_f32_e32 v67, v69, v67
	v_mul_f32_e32 v69, v68, v67
	v_fma_f32 v70, -v66, v69, v68
	v_fmac_f32_e32 v69, v70, v67
	v_fma_f32 v66, -v66, v69, v68
	v_div_fmas_f32 v66, v66, v67, v69
	v_div_fixup_f32 v64, v66, v65, v64
	s_and_b64 vcc, exec, s[4:5]
	v_mul_f32_e32 v61, v61, v64
	s_cbranch_vccz .LBB0_252
	s_andn2_b64 vcc, exec, s[0:1]
	s_cbranch_vccz .LBB0_253

.LBB0_232:
	v_mov_b32_e32 v48, v107
	ds_bpermute_b32 v49, v193, v155
	s_waitcnt lgkmcnt(0)
	v_add_f32_e32 v49, v155, v49
	ds_bpermute_b32 v50, v194, v49
	s_waitcnt lgkmcnt(0)
	v_add_f32_e32 v49, v49, v50
	v_mul_f32_e32 v48, 0xbfb8aa3b, v48
	v_exp_f32_e32 v48, v48
	s_nop 0
	v_add_f32_e32 v48, 1.0, v48
	v_rcp_f32_e32 v48, v48
	s_nop 0
	v_div_scale_f32 v50, s[0:1], v49, v49, v48
	v_rcp_f32_e32 v51, v50
	v_div_scale_f32 v52, vcc, v48, v49, v48
	s_mov_b64 s[0:1], -1
	v_fma_f32 v53, -v50, v51, 1.0
	v_fmac_f32_e32 v51, v53, v51
	v_mul_f32_e32 v53, v52, v51
	v_fma_f32 v54, -v50, v53, v52
	v_fmac_f32_e32 v53, v54, v51
	v_fma_f32 v50, -v50, v53, v52
	v_div_fmas_f32 v50, v50, v51, v53
	v_div_fixup_f32 v48, v50, v49, v48
	s_and_b64 vcc, exec, s[4:5]
	v_mul_f32_e32 v45, v45, v48
	s_cbranch_vccz .LBB0_259
	s_andn2_b64 vcc, exec, s[0:1]
	s_cbranch_vccz .LBB0_260

.LBB0_427:
	s_lshl_b32 s29, s2, 6
	s_waitcnt lgkmcnt(0)
	s_barrier
	v_or_b32_e32 v136, s29, v172
	ds_read_b128 v[94:97], v183
	ds_read_b128 v[84:87], v183 offset:16
	ds_read_b128 v[98:101], v121
	ds_read_b128 v[88:91], v121 offset:16
	ds_read_b128 v[102:105], v121 offset:512
	ds_read_b128 v[106:109], v121 offset:1024
	ds_read_b128 v[110:113], v121 offset:1536
	s_waitcnt vmcnt(0) lgkmcnt(0)
	v_lshlrev_b32_e32 v92, 16, v32
	v_and_b32_e32 v32, 0xffff0000, v32
	v_cmp_eq_u32_e32 vcc, 0, v136
	v_lshlrev_b32_e32 v130, 16, v40
	v_and_b32_e32 v131, 0xffff0000, v40
	v_cndmask_b32_e64 v93, v32, 0, vcc
	v_cndmask_b32_e64 v92, v92, 0, vcc
	v_lshlrev_b32_e32 v32, 16, v36
	v_and_b32_e32 v36, 0xffff0000, v36
	v_cndmask_b32_e64 v115, v36, 0, vcc
	v_cndmask_b32_e64 v114, v32, 0, vcc
	v_pk_fma_f32 v[134:135], v[92:93], v[98:99], v[94:95]
	v_lshlrev_b32_e32 v132, 16, v44
	v_pk_fma_f32 v[134:135], v[114:115], v[102:103], v[134:135]
	v_and_b32_e32 v133, 0xffff0000, v44
	v_pk_fma_f32 v[134:135], v[106:107], v[130:131], v[134:135]
	v_lshlrev_b32_e32 v36, 16, v28
	v_pk_fma_f32 v[144:145], v[110:111], v[132:133], v[134:135]
	v_and_b32_e32 v28, 0xffff0000, v28
	v_cmp_lt_u32_e64 s[18:19], 2, v136
	v_mul_f32_e32 v32, 0xbfb8aa3b, v144
	v_exp_f32_e32 v32, v32
	v_cndmask_b32_e64 v133, 0, v28, s[18:19]
	v_cndmask_b32_e64 v132, 0, v36, s[18:19]
	v_pk_fma_f32 v[94:95], v[132:133], v[98:99], v[94:95]
	v_add_f32_e32 v32, 1.0, v32
	v_pk_fma_f32 v[92:93], v[92:93], v[102:103], v[94:95]
	v_rcp_f32_e32 v102, v32
	v_pk_fma_f32 v[92:93], v[114:115], v[106:107], v[92:93]
	v_mul_f32_e32 v36, 0xbfb8aa3b, v145
	v_pk_fma_f32 v[98:99], v[110:111], v[130:131], v[92:93]
	v_exp_f32_e32 v36, v36
	v_mul_f32_e32 v28, 0xbfb8aa3b, v98
	v_exp_f32_e32 v28, v28
	v_mul_f32_e32 v32, 0xbfb8aa3b, v99
	v_exp_f32_e32 v32, v32
	v_lshlrev_b32_e32 v40, 16, v41
	v_add_f32_e32 v28, 1.0, v28
	v_rcp_f32_e32 v106, v28
	v_add_f32_e32 v28, 1.0, v32
	v_rcp_f32_e32 v107, v28
	v_add_f32_e32 v28, 1.0, v36
	v_rcp_f32_e32 v103, v28
	v_lshlrev_b32_e32 v28, 16, v33
	v_and_b32_e32 v32, 0xffff0000, v33
	v_cndmask_b32_e64 v33, v32, 0, vcc
	v_cndmask_b32_e64 v32, v28, 0, vcc
	v_lshlrev_b32_e32 v28, 16, v37
	v_and_b32_e32 v36, 0xffff0000, v37
	v_cndmask_b32_e64 v37, v36, 0, vcc
	v_cndmask_b32_e64 v36, v28, 0, vcc
	v_lshlrev_b32_e32 v28, 16, v29
	v_and_b32_e32 v29, 0xffff0000, v29
	v_cndmask_b32_e64 v29, 0, v29, s[18:19]
	v_cndmask_b32_e64 v28, 0, v28, s[18:19]
	v_pk_fma_f32 v[28:29], v[28:29], v[100:101], v[96:97]
	v_and_b32_e32 v41, 0xffff0000, v41
	v_pk_fma_f32 v[28:29], v[32:33], v[104:105], v[28:29]
	v_pk_mul_f32 v[98:99], v[98:99], v[106:107]
	v_pk_fma_f32 v[28:29], v[36:37], v[108:109], v[28:29]
	v_pk_fma_f32 v[106:107], v[32:33], v[100:101], v[96:97]
	v_pk_fma_f32 v[28:29], v[112:113], v[40:41], v[28:29]
	v_pk_fma_f32 v[106:107], v[36:37], v[104:105], v[106:107]
	v_mul_f32_e32 v32, 0xbfb8aa3b, v28
	v_mul_f32_e32 v33, 0xbfb8aa3b, v29
	v_exp_f32_e32 v32, v32
	v_exp_f32_e32 v33, v33
	v_lshlrev_b32_e32 v44, 16, v45
	v_and_b32_e32 v45, 0xffff0000, v45
	v_pk_fma_f32 v[106:107], v[108:109], v[40:41], v[106:107]
	v_add_f32_e32 v32, 1.0, v32
	v_pk_fma_f32 v[44:45], v[112:113], v[44:45], v[106:107]
	v_add_f32_e32 v33, 1.0, v33
	v_mul_f32_e32 v37, 0xbfb8aa3b, v45
	v_rcp_f32_e32 v32, v32
	v_rcp_f32_e32 v33, v33
	v_exp_f32_e32 v37, v37
	ds_read_b128 v[92:95], v121 offset:528
	ds_read_b128 v[130:133], v121 offset:1040
	ds_read_b128 v[134:137], v121 offset:1552
	v_pk_mul_f32 v[32:33], v[28:29], v[32:33]
	v_add_f32_e32 v28, 1.0, v37
	v_rcp_f32_e32 v37, v28
	v_lshlrev_b32_e32 v28, 16, v34
	v_and_b32_e32 v29, 0xffff0000, v34
	v_cndmask_b32_e64 v29, v29, 0, vcc
	v_cndmask_b32_e64 v28, v28, 0, vcc
	v_lshlrev_b32_e32 v34, 16, v38
	v_and_b32_e32 v38, 0xffff0000, v38
	v_cndmask_b32_e64 v41, v38, 0, vcc
	v_cndmask_b32_e64 v40, v34, 0, vcc
	v_pk_fma_f32 v[104:105], v[28:29], v[88:89], v[84:85]
	v_lshlrev_b32_e32 v96, 16, v42
	v_and_b32_e32 v97, 0xffff0000, v42
	s_waitcnt lgkmcnt(2)
	v_pk_fma_f32 v[104:105], v[40:41], v[92:93], v[104:105]
	v_lshlrev_b32_e32 v100, 16, v46
	v_and_b32_e32 v101, 0xffff0000, v46
	s_waitcnt lgkmcnt(1)
	v_pk_fma_f32 v[104:105], v[130:131], v[96:97], v[104:105]
	v_lshlrev_b32_e32 v38, 16, v30
	v_and_b32_e32 v30, 0xffff0000, v30
	s_waitcnt lgkmcnt(0)
	v_pk_fma_f32 v[100:101], v[134:135], v[100:101], v[104:105]
	v_cndmask_b32_e64 v105, 0, v30, s[18:19]
	v_cndmask_b32_e64 v104, 0, v38, s[18:19]
	v_pk_fma_f32 v[84:85], v[104:105], v[88:89], v[84:85]
	v_mul_f32_e32 v34, 0xbfb8aa3b, v100
	v_pk_fma_f32 v[28:29], v[28:29], v[92:93], v[84:85]
	v_exp_f32_e32 v34, v34
	v_pk_fma_f32 v[28:29], v[40:41], v[130:131], v[28:29]
	v_mul_f32_e32 v106, 0xbfb8aa3b, v44
	v_pk_fma_f32 v[28:29], v[134:135], v[96:97], v[28:29]
	v_exp_f32_e32 v36, v106
	v_mul_f32_e32 v30, 0xbfb8aa3b, v28
	v_exp_f32_e32 v38, v30
	v_add_f32_e32 v30, 1.0, v34
	v_add_f32_e32 v36, 1.0, v36
	v_rcp_f32_e32 v36, v36
	v_add_f32_e32 v34, 1.0, v38
	v_mul_f32_e32 v38, 0xbfb8aa3b, v29
	v_exp_f32_e32 v38, v38
	v_mul_f32_e32 v40, 0xbfb8aa3b, v101
	v_exp_f32_e32 v42, v40
	v_rcp_f32_e32 v40, v34
	v_add_f32_e32 v34, 1.0, v38
	v_rcp_f32_e32 v41, v34
	v_lshlrev_b32_e32 v34, 16, v35
	v_and_b32_e32 v35, 0xffff0000, v35
	v_cndmask_b32_e64 v35, v35, 0, vcc
	v_cndmask_b32_e64 v34, v34, 0, vcc
	v_lshlrev_b32_e32 v38, 16, v39
	v_and_b32_e32 v39, 0xffff0000, v39
	v_pk_mul_f32 v[36:37], v[44:45], v[36:37]
	v_cndmask_b32_e64 v39, v39, 0, vcc
	v_cndmask_b32_e64 v38, v38, 0, vcc
	v_lshlrev_b32_e32 v44, 16, v47
	v_and_b32_e32 v45, 0xffff0000, v47
	v_pk_fma_f32 v[46:47], v[34:35], v[90:91], v[86:87]
	v_add_f32_e32 v84, 1.0, v42
	v_lshlrev_b32_e32 v42, 16, v43
	v_and_b32_e32 v43, 0xffff0000, v43
	v_pk_fma_f32 v[46:47], v[38:39], v[94:95], v[46:47]
	v_rcp_f32_e32 v30, v30
	v_pk_fma_f32 v[46:47], v[132:133], v[42:43], v[46:47]
	v_pk_mul_f32 v[40:41], v[28:29], v[40:41]
	v_pk_fma_f32 v[44:45], v[136:137], v[44:45], v[46:47]
	v_pk_mul_f32 v[102:103], v[144:145], v[102:103]
	v_mul_f32_e32 v46, 0xbfb8aa3b, v44
	v_exp_f32_e32 v85, v46
	v_lshlrev_b32_e32 v46, 16, v31
	v_and_b32_e32 v31, 0xffff0000, v31
	v_cndmask_b32_e64 v47, 0, v31, s[18:19]
	v_cndmask_b32_e64 v46, 0, v46, s[18:19]
	v_pk_fma_f32 v[46:47], v[46:47], v[90:91], v[86:87]
	v_cvt_pk_bf16_f32 v28, v98, v99
	v_pk_fma_f32 v[34:35], v[34:35], v[94:95], v[46:47]
	v_cvt_pk_bf16_f32 v29, v32, v33
	v_pk_fma_f32 v[34:35], v[38:39], v[132:133], v[34:35]
	v_add_f32_e32 v38, 1.0, v85
	v_pk_fma_f32 v[34:35], v[136:137], v[42:43], v[34:35]
	v_rcp_f32_e32 v38, v38
	v_mul_f32_e32 v31, 0xbfb8aa3b, v34
	v_exp_f32_e32 v39, v31
	v_mul_f32_e32 v42, 0xbfb8aa3b, v35
	v_exp_f32_e32 v43, v42
	v_mul_f32_e32 v42, 0xbfb8aa3b, v45
	v_exp_f32_e32 v46, v42
	v_add_f32_e32 v39, 1.0, v39
	v_rcp_f32_e32 v42, v39
	v_add_f32_e32 v39, 1.0, v43
	v_rcp_f32_e32 v43, v39
	v_add_f32_e32 v39, 1.0, v46
	v_rcp_f32_e32 v31, v84
	v_rcp_f32_e32 v39, v39
	v_pk_mul_f32 v[34:35], v[34:35], v[42:43]
	v_cvt_pk_bf16_f32 v32, v102, v103
	v_pk_mul_f32 v[46:47], v[100:101], v[30:31]
	v_pk_mul_f32 v[38:39], v[44:45], v[38:39]
	v_cvt_pk_bf16_f32 v30, v40, v41
	v_cvt_pk_bf16_f32 v31, v34, v35
	v_cvt_pk_bf16_f32 v33, v36, v37
	v_cvt_pk_bf16_f32 v34, v46, v47
	v_cvt_pk_bf16_f32 v35, v38, v39
	ds_write_b128 v184, v[28:31]
	ds_write_b128 v184, v[32:35] offset:272
	v_lshlrev_b32_e32 v28, 16, v24
	v_and_b32_e32 v24, 0xffff0000, v24
	v_cndmask_b32_e64 v106, 0, v24, s[18:19]
	v_and_b32_e32 v24, 0xffff0000, v25
	v_cndmask_b32_e64 v44, 0, v28, s[18:19]
	v_lshlrev_b32_e32 v28, 16, v25
	v_lshlrev_b32_e32 v25, 16, v26
	v_cndmask_b32_e64 v110, 0, v24, s[18:19]
	v_and_b32_e32 v24, 0xffff0000, v26
	v_lshlrev_b32_e32 v45, 16, v8
	v_cndmask_b32_e64 v112, 0, v25, s[18:19]
	v_lshlrev_b32_e32 v25, 16, v27
	v_cndmask_b32_e64 v114, 0, v24, s[18:19]
	v_and_b32_e32 v24, 0xffff0000, v27
	v_cndmask_b32_e64 v130, v45, 0, vcc
	v_cndmask_b32_e64 v108, 0, v28, s[18:19]
	v_cndmask_b32_e64 v84, 0, v25, s[18:19]
	v_cndmask_b32_e64 v46, 0, v24, s[18:19]
	ds_read_b128 v[86:89], v185
	ds_read_b128 v[32:35], v185 offset:16
	ds_read_b128 v[90:93], v121 offset:2560
	ds_read_b128 v[40:43], v121 offset:2576
	ds_read_b128 v[94:97], v121 offset:3072
	ds_read_b128 v[36:39], v121 offset:3088
	ds_read_b128 v[98:101], v121 offset:3584
	ds_read_b128 v[24:27], v121 offset:3600
	ds_read_b128 v[102:105], v121 offset:4096
	ds_read_b128 v[28:31], v121 offset:4112
	v_and_b32_e32 v8, 0xffff0000, v8
	v_mov_b32_e32 v45, v130
	s_waitcnt lgkmcnt(7)
	v_mov_b32_e32 v146, v90
	s_waitcnt lgkmcnt(5)
	v_mov_b32_e32 v147, v94
	v_cndmask_b32_e64 v131, v8, 0, vcc
	v_lshlrev_b32_e32 v8, 16, v12
	v_pk_mul_f32 v[44:45], v[44:45], v[146:147]
	v_cndmask_b32_e64 v132, v8, 0, vcc
	v_add_f32_e32 v8, v86, v44
	v_add_f32_e32 v8, v8, v45
	v_mov_b32_e32 v107, v131
	v_mov_b32_e32 v44, v91
	v_mov_b32_e32 v45, v95
	v_and_b32_e32 v12, 0xffff0000, v12
	v_lshlrev_b32_e32 v134, 16, v16
	v_pk_mul_f32 v[44:45], v[106:107], v[44:45]
	v_cndmask_b32_e64 v133, v12, 0, vcc
	v_pk_fma_f32 v[144:145], v[130:131], v[90:91], v[86:87]
	v_add_f32_e32 v12, v87, v44
	v_mov_b32_e32 v86, v132
	s_waitcnt lgkmcnt(1)
	v_mov_b32_e32 v87, v102
	v_mov_b32_e32 v90, v98
	v_mov_b32_e32 v91, v134
	v_pk_mul_f32 v[86:87], v[86:87], v[90:91]
	v_and_b32_e32 v135, 0xffff0000, v16
	v_add_f32_e32 v8, v8, v86
	v_add_f32_e32 v8, v8, v87
	v_mul_f32_e32 v16, 0xbfb8aa3b, v8
	v_exp_f32_e32 v16, v16
	v_add_f32_e32 v12, v12, v45
	v_pk_fma_f32 v[44:45], v[132:133], v[94:95], v[144:145]
	v_lshlrev_b32_e32 v136, 16, v20
	v_and_b32_e32 v137, 0xffff0000, v20
	v_pk_fma_f32 v[44:45], v[98:99], v[134:135], v[44:45]
	v_add_f32_e32 v16, 1.0, v16
	v_pk_fma_f32 v[44:45], v[102:103], v[136:137], v[44:45]
	v_mov_b32_e32 v86, v133
	v_mul_f32_e32 v20, 0xbfb8aa3b, v44
	v_mov_b32_e32 v87, v103
	v_mov_b32_e32 v134, v99
	v_rcp_f32_e32 v16, v16
	v_exp_f32_e32 v20, v20
	v_pk_mul_f32 v[86:87], v[86:87], v[134:135]
	v_mul_f32_e32 v47, 0xbfb8aa3b, v45
	v_add_f32_e32 v12, v12, v86
	v_add_f32_e32 v12, v12, v87
	v_mul_f32_e32 v8, v8, v16
	v_add_f32_e32 v16, 1.0, v20
	v_mul_f32_e32 v20, 0xbfb8aa3b, v12
	v_exp_f32_e32 v20, v20
	v_rcp_f32_e32 v86, v16
	v_exp_f32_e32 v47, v47
	v_mul_f32_e32 v94, 0x3db504f3, v8
	v_add_f32_e32 v16, 1.0, v20
	v_rcp_f32_e32 v16, v16
	v_add_f32_e32 v20, 1.0, v47
	v_rcp_f32_e32 v87, v20
	v_mov_b32_e32 v90, v92
	v_mul_f32_e32 v8, v12, v16
	v_mul_f32_e32 v95, 0x3db504f3, v8
	v_lshlrev_b32_e32 v8, 16, v9
	v_cndmask_b32_e64 v8, v8, 0, vcc
	v_and_b32_e32 v9, 0xffff0000, v9
	v_mov_b32_e32 v109, v8
	v_mov_b32_e32 v91, v96
	v_cndmask_b32_e64 v9, v9, 0, vcc
	v_pk_mul_f32 v[90:91], v[108:109], v[90:91]
	v_pk_mul_f32 v[44:45], v[44:45], v[86:87]
	v_pk_fma_f32 v[86:87], v[8:9], v[92:93], v[88:89]
	v_add_f32_e32 v8, v88, v90
	v_add_f32_e32 v47, v8, v91
	v_mov_b32_e32 v111, v9
	v_mov_b32_e32 v8, v93
	v_mov_b32_e32 v9, v97
	v_lshlrev_b32_e32 v12, 16, v13
	v_and_b32_e32 v13, 0xffff0000, v13
	v_pk_mul_f32 v[8:9], v[110:111], v[8:9]
	v_cndmask_b32_e64 v13, v13, 0, vcc
	v_cndmask_b32_e64 v12, v12, 0, vcc
	v_lshlrev_b32_e32 v16, 16, v17
	v_add_f32_e32 v8, v89, v8
	v_add_f32_e32 v85, v8, v9
	v_pk_fma_f32 v[8:9], v[12:13], v[96:97], v[86:87]
	v_mov_b32_e32 v86, v12
	v_mov_b32_e32 v87, v104
	v_mov_b32_e32 v88, v100
	v_mov_b32_e32 v89, v16
	v_pk_mul_f32 v[86:87], v[86:87], v[88:89]
	v_and_b32_e32 v17, 0xffff0000, v17
	v_add_f32_e32 v12, v47, v86
	v_add_f32_e32 v47, v12, v87
	v_lshlrev_b32_e32 v20, 16, v21
	v_and_b32_e32 v21, 0xffff0000, v21
	v_pk_fma_f32 v[8:9], v[100:101], v[16:17], v[8:9]
	v_mul_f32_e32 v16, 0xbfb8aa3b, v47
	v_mov_b32_e32 v12, v13
	v_mov_b32_e32 v13, v105
	v_exp_f32_e32 v86, v16
	v_mov_b32_e32 v16, v101
	v_pk_fma_f32 v[8:9], v[104:105], v[20:21], v[8:9]
	v_pk_mul_f32 v[12:13], v[12:13], v[16:17]
	v_mul_f32_e32 v17, 0xbfb8aa3b, v8
	v_exp_f32_e32 v17, v17
	v_add_f32_e32 v12, v85, v12
	v_add_f32_e32 v20, v12, v13
	v_mul_f32_e32 v13, 0xbfb8aa3b, v20
	v_add_f32_e32 v12, 1.0, v17
	v_exp_f32_e32 v13, v13
	v_mul_f32_e32 v17, 0xbfb8aa3b, v9
	v_exp_f32_e32 v17, v17
	v_rcp_f32_e32 v12, v12
	v_add_f32_e32 v13, 1.0, v13
	v_rcp_f32_e32 v21, v13
	v_add_f32_e32 v13, 1.0, v17
	v_rcp_f32_e32 v13, v13
	v_add_f32_e32 v16, 1.0, v86
	v_rcp_f32_e32 v16, v16
	v_mov_b32_e32 v90, v40
	v_pk_mul_f32 v[8:9], v[8:9], v[12:13]
	v_lshlrev_b32_e32 v12, 16, v10
	v_and_b32_e32 v10, 0xffff0000, v10
	v_cndmask_b32_e64 v13, v10, 0, vcc
	v_cndmask_b32_e64 v12, v12, 0, vcc
	v_mul_f32_e32 v16, v47, v16
	v_pk_fma_f32 v[88:89], v[12:13], v[40:41], v[32:33]
	v_mov_b32_e32 v113, v12
	v_mov_b32_e32 v115, v13
	v_mov_b32_e32 v12, v41
	v_mov_b32_e32 v13, v37
	v_mul_f32_e32 v92, 0x3db504f3, v16
	v_mul_f32_e32 v16, v20, v21
	v_lshlrev_b32_e32 v10, 16, v14
	v_and_b32_e32 v14, 0xffff0000, v14
	v_mov_b32_e32 v91, v36
	v_pk_mul_f32 v[12:13], v[114:115], v[12:13]
	v_mul_f32_e32 v93, 0x3db504f3, v16
	v_cndmask_b32_e64 v17, v14, 0, vcc
	v_cndmask_b32_e64 v16, v10, 0, vcc
	v_lshlrev_b32_e32 v20, 16, v18
	v_pk_mul_f32 v[90:91], v[112:113], v[90:91]
	v_add_f32_e32 v12, v33, v12
	v_add_f32_e32 v10, v32, v90
	v_add_f32_e32 v14, v12, v13
	v_pk_fma_f32 v[12:13], v[16:17], v[36:37], v[88:89]
	v_mov_b32_e32 v32, v16
	s_waitcnt lgkmcnt(0)
	v_mov_b32_e32 v33, v28
	v_mov_b32_e32 v36, v24
	v_mov_b32_e32 v37, v20
	v_add_f32_e32 v10, v10, v91
	v_pk_mul_f32 v[32:33], v[32:33], v[36:37]
	v_and_b32_e32 v21, 0xffff0000, v18
	v_add_f32_e32 v10, v10, v32
	v_add_f32_e32 v10, v10, v33
	v_mul_f32_e32 v18, 0xbfb8aa3b, v10
	v_exp_f32_e32 v18, v18
	v_pk_fma_f32 v[12:13], v[24:25], v[20:21], v[12:13]
	v_mov_b32_e32 v16, v17
	v_mov_b32_e32 v17, v29
	v_mov_b32_e32 v20, v25
	v_pk_mul_f32 v[16:17], v[16:17], v[20:21]
	v_add_f32_e32 v18, 1.0, v18
	v_add_f32_e32 v14, v14, v16
	v_lshlrev_b32_e32 v86, 16, v22
	v_and_b32_e32 v87, 0xffff0000, v22
	v_rcp_f32_e32 v18, v18
	v_add_f32_e32 v14, v14, v17
	v_pk_fma_f32 v[12:13], v[28:29], v[86:87], v[12:13]
	v_mul_f32_e32 v17, 0xbfb8aa3b, v14
	v_mul_f32_e32 v20, 0xbfb8aa3b, v12
	v_exp_f32_e32 v17, v17
	v_exp_f32_e32 v20, v20
	v_mul_f32_e32 v10, v10, v18
	v_mul_f32_e32 v18, 0xbfb8aa3b, v13
	v_exp_f32_e32 v18, v18
	v_add_f32_e32 v17, 1.0, v17
	v_add_f32_e32 v16, 1.0, v20
	v_rcp_f32_e32 v20, v17
	v_add_f32_e32 v17, 1.0, v18
	v_rcp_f32_e32 v16, v16
	v_rcp_f32_e32 v17, v17
	v_mul_f32_e32 v24, 0x3db504f3, v10
	v_mul_f32_e32 v10, v14, v20
	v_mul_f32_e32 v25, 0x3db504f3, v10
	v_lshlrev_b32_e32 v10, 16, v11
	v_cndmask_b32_e64 v10, v10, 0, vcc
	v_pk_mul_f32 v[12:13], v[12:13], v[16:17]
	v_and_b32_e32 v11, 0xffff0000, v11
	v_lshlrev_b32_e32 v16, 16, v23
	v_and_b32_e32 v17, 0xffff0000, v23
	v_mov_b32_e32 v85, v10
	v_mov_b32_e32 v22, v42
	v_mov_b32_e32 v23, v38
	s_mov_b32 s0, s2
	s_mov_b32 s2, 0x3db504f3
	v_cndmask_b32_e64 v11, v11, 0, vcc
	v_pk_mul_f32 v[22:23], v[84:85], v[22:23]
	v_pk_mul_f32 v[20:21], v[12:13], s[2:3] op_sel_hi:[1,0]
	v_lshlrev_b32_e32 v12, 16, v15
	v_and_b32_e32 v13, 0xffff0000, v15
	v_lshlrev_b32_e32 v14, 16, v19
	v_and_b32_e32 v15, 0xffff0000, v19
	v_pk_fma_f32 v[18:19], v[10:11], v[42:43], v[34:35]
	v_add_f32_e32 v10, v34, v22
	v_add_f32_e32 v28, v10, v23
	v_mov_b32_e32 v47, v11
	v_mov_b32_e32 v10, v43
	v_mov_b32_e32 v11, v39
	v_pk_mul_f32 v[10:11], v[46:47], v[10:11]
	v_cndmask_b32_e64 v13, v13, 0, vcc
	v_cndmask_b32_e64 v12, v12, 0, vcc
	v_add_f32_e32 v10, v35, v10
	v_add_f32_e32 v29, v10, v11
	v_pk_fma_f32 v[10:11], v[12:13], v[38:39], v[18:19]
	v_mov_b32_e32 v18, v12
	v_mov_b32_e32 v19, v30
	v_mov_b32_e32 v22, v26
	v_mov_b32_e32 v23, v14
	v_pk_mul_f32 v[18:19], v[18:19], v[22:23]
	v_pk_fma_f32 v[10:11], v[26:27], v[14:15], v[10:11]
	v_add_f32_e32 v12, v28, v18
	v_add_f32_e32 v18, v12, v19
	v_mul_f32_e32 v14, 0xbfb8aa3b, v18
	v_mov_b32_e32 v12, v13
	v_mov_b32_e32 v13, v31
	v_exp_f32_e32 v19, v14
	v_mov_b32_e32 v14, v27
	v_pk_fma_f32 v[10:11], v[30:31], v[16:17], v[10:11]
	v_pk_mul_f32 v[12:13], v[12:13], v[14:15]
	v_mul_f32_e32 v15, 0xbfb8aa3b, v10
	v_exp_f32_e32 v15, v15
	v_add_f32_e32 v12, v29, v12
	v_add_f32_e32 v16, v12, v13
	v_mul_f32_e32 v13, 0xbfb8aa3b, v16
	v_add_f32_e32 v12, 1.0, v15
	v_exp_f32_e32 v13, v13
	v_mul_f32_e32 v15, 0xbfb8aa3b, v11
	v_exp_f32_e32 v15, v15
	v_add_f32_e32 v14, 1.0, v19
	v_rcp_f32_e32 v14, v14
	v_add_f32_e32 v13, 1.0, v13
	v_rcp_f32_e32 v17, v13
	v_add_f32_e32 v13, 1.0, v15
	v_rcp_f32_e32 v12, v12
	v_rcp_f32_e32 v13, v13
	v_mul_f32_e32 v14, v18, v14
	v_mul_f32_e32 v22, 0x3db504f3, v14
	v_mul_f32_e32 v14, v16, v17
	v_mul_f32_e32 v23, 0x3db504f3, v14
	v_pk_mul_f32 v[10:11], v[10:11], v[12:13]
	v_pk_mul_f32 v[44:45], v[44:45], s[2:3] op_sel_hi:[1,0]
	v_pk_mul_f32 v[8:9], v[8:9], s[2:3] op_sel_hi:[1,0]
	v_pk_mul_f32 v[18:19], v[10:11], s[2:3] op_sel_hi:[1,0]
	v_cvt_pk_bf16_f32 v10, v94, v95
	v_cvt_pk_bf16_f32 v11, v92, v93
	v_cvt_pk_bf16_f32 v12, v24, v25
	v_cvt_pk_bf16_f32 v13, v22, v23
	v_cvt_pk_bf16_f32 v14, v44, v45
	v_cvt_pk_bf16_f32 v15, v8, v9
	v_cvt_pk_bf16_f32 v16, v20, v21
	v_cvt_pk_bf16_f32 v17, v18, v19
	ds_write_b128 v184, v[10:13] offset:17408
	ds_write_b128 v184, v[14:17] offset:17680
	v_mov_b32_e32 v84, v248
	v_mov_b32_e32 v85, v249
	v_add_u32_e32 v12, 0x8800, v198
	v_cvt_pk_bf16_f32 v8, v92, v8
	v_cvt_pk_bf16_f32 v9, v93, v9
	s_add_i32 s2, s0, 1
	ds_write2_b32 v12, v8, v9 offset0:72 offset1:108
	v_cvt_pk_bf16_f32 v8, v24, v20
	v_cvt_pk_bf16_f32 v9, v25, v21
	s_lshl_b32 s1, s2, 6
	ds_write2_b32 v12, v8, v9 offset0:144 offset1:180
	v_cvt_pk_bf16_f32 v8, v22, v18
	s_cmp_lg_u32 s0, 31
	v_cvt_pk_bf16_f32 v10, v94, v44
	v_cvt_pk_bf16_f32 v11, v95, v45
	ds_write_b32 v198, v8 offset:35680
	v_cvt_pk_bf16_f32 v8, v23, v19
	s_cselect_b32 s0, s1, 0x7c0
	ds_write2_b32 v12, v10, v11 offset1:36
	ds_write_b32 v199, v8 offset:34816
	ds_write_b16 v186, v4 offset:53248
	ds_write_b16_d16_hi v186, v4 offset:53392
	ds_write_b16 v186, v5 offset:53536
	ds_write_b16_d16_hi v186, v5 offset:53680
	ds_write_b16 v186, v6 offset:53824
	ds_write_b16_d16_hi v186, v6 offset:53968
	ds_write_b16 v186, v7 offset:54112
	ds_write_b16_d16_hi v186, v7 offset:54256
	ds_write_b16 v186, v0 offset:54400
	ds_write_b16_d16_hi v186, v0 offset:54544
	ds_write_b16 v186, v1 offset:54688
	ds_write_b16_d16_hi v186, v1 offset:54832
	ds_write_b16 v186, v2 offset:54976
	ds_write_b16_d16_hi v186, v2 offset:55120
	ds_write_b16 v186, v3 offset:55264
	ds_write_b16_d16_hi v186, v3 offset:55408
	v_add_u32_e32 v4, s0, v173
	v_max_i32_e32 v0, 0, v4
	v_readlane_b32 s1, v253, 58
	v_readlane_b32 s18, v253, 56
	s_nop 0
	v_add_f32_e32 v92, v196, v84
	v_add_u32_e32 v0, s1, v0
	v_ashrrev_i32_e32 v1, 31, v0
	v_lshlrev_b64 v[0:1], 10, v[0:1]
	v_lshl_add_u64 v[2:3], v[116:117], 0, v[0:1]
	v_lshl_add_u64 v[0:1], v[118:119], 0, v[0:1]
	global_load_dwordx4 v[28:31], v[2:3], off
	global_load_dwordx4 v[24:27], v[0:1], off
	v_max_i32_e32 v0, -1, v4
	v_add_u32_e32 v0, s18, v0
	v_ashrrev_i32_e32 v1, 31, v0
	v_lshlrev_b64 v[0:1], 10, v[0:1]
	v_lshl_add_u64 v[2:3], v[116:117], 0, v[0:1]
	v_lshl_add_u64 v[0:1], v[118:119], 0, v[0:1]
	global_load_dwordx4 v[32:35], v[2:3], off
	global_load_dwordx4 v[8:11], v[0:1], off
	v_max_i32_e32 v0, -2, v4
	v_readlane_b32 s18, v253, 57
	s_nop 1
	v_add_u32_e32 v0, s18, v0
	v_ashrrev_i32_e32 v1, 31, v0
	v_lshlrev_b64 v[0:1], 10, v[0:1]
	v_lshl_add_u64 v[2:3], v[116:117], 0, v[0:1]
	v_lshl_add_u64 v[0:1], v[118:119], 0, v[0:1]
	global_load_dwordx4 v[36:39], v[2:3], off
	global_load_dwordx4 v[12:15], v[0:1], off
	v_add_u32_e32 v0, s0, v120
	v_ashrrev_i32_e32 v1, 31, v0
	v_lshlrev_b64 v[0:1], 10, v[0:1]
	v_lshl_add_u64 v[2:3], v[116:117], 0, v[0:1]
	v_lshl_add_u64 v[0:1], v[118:119], 0, v[0:1]
	global_load_dwordx4 v[40:43], v[2:3], off
	global_load_dwordx4 v[16:19], v[0:1], off
	v_max_i32_e32 v0, -4, v4
	v_readlane_b32 s18, v253, 59
	s_nop 1
	v_add_u32_e32 v0, s18, v0
	v_ashrrev_i32_e32 v1, 31, v0
	v_lshlrev_b64 v[0:1], 10, v[0:1]
	v_lshl_add_u64 v[2:3], v[116:117], 0, v[0:1]
	v_lshl_add_u64 v[0:1], v[118:119], 0, v[0:1]
	global_load_dwordx4 v[44:47], v[2:3], off
	global_load_dwordx4 v[20:23], v[0:1], off
	v_add_f32_e32 v2, v204, v85
	s_mov_b32 s18, 0xbfb8aa3b
	v_mul_f32_e64 v0, |v2|, s18
	v_exp_f32_e32 v0, v0
	s_add_i32 s18, s0, s1
	s_mov_b32 s0, 0x800000
	v_min_f32_e32 v2, 0, v2
	v_add_f32_e32 v0, 1.0, v0
	v_cmp_gt_f32_e32 vcc, s0, v0
	s_mov_b32 s0, 0x3f317217
	v_or_b32_e32 v84, s18, v170
	v_cndmask_b32_e64 v1, 0, 32, vcc
	v_ldexp_f32 v0, v0, v1
	v_log_f32_e32 v3, v0
	v_ashrrev_i32_e32 v85, 31, v84
	v_lshlrev_b64 v[0:1], 10, v[84:85]
	v_lshlrev_b64 v[84:85], 7, v[84:85]
	v_mul_f32_e32 v4, 0x3f317217, v3
	v_fma_f32 v4, v3, s0, -v4
	v_fmac_f32_e32 v4, 0x3377d1cf, v3
	s_mov_b32 s0, 0x7f800000
	v_fmac_f32_e32 v4, 0x3f317217, v3
	v_cmp_lt_f32_e64 s[0:1], |v3|, s0
	v_lshl_add_u64 v[0:1], s[22:23], 0, v[0:1]
	v_lshl_add_u64 v[84:85], s[24:25], 0, v[84:85]
	v_cndmask_b32_e64 v3, v3, v4, s[0:1]
	v_cndmask_b32_e32 v4, 0, v225, vcc
	v_sub_f32_e32 v3, v3, v4
	v_sub_f32_e32 v250, v2, v3
	v_readlane_b32 s0, v253, 41
	v_readlane_b32 s1, v253, 42
	global_load_dwordx4 v[4:7], v[0:1], off
	s_nop 0
	global_load_dwordx4 v[0:3], v[0:1], off offset:16
	v_or_b32_e32 v86, s18, v171
	v_ashrrev_i32_e32 v87, 31, v86
	v_lshlrev_b64 v[88:89], 10, v[86:87]
	v_lshl_add_u64 v[88:89], v[122:123], 0, v[88:89]
	v_or_b32_e32 v90, 16, v86
	v_ashrrev_i32_e32 v91, 31, v90
	v_lshlrev_b64 v[90:91], 10, v[90:91]
	v_lshl_add_u64 v[90:91], v[122:123], 0, v[90:91]
	global_load_dword v196, v[84:85], off
	global_load_dword v204, v[84:85], off offset:16
	global_load_dwordx2 v[130:131], v[88:89], off
	global_load_dwordx2 v[132:133], v[90:91], off
	v_or_b32_e32 v84, 32, v86
	v_ashrrev_i32_e32 v85, 31, v84
	v_or_b32_e32 v86, 48, v86
	v_lshlrev_b64 v[84:85], 10, v[84:85]
	v_lshl_add_u64 v[84:85], v[122:123], 0, v[84:85]
	v_ashrrev_i32_e32 v87, 31, v86
	v_lshlrev_b64 v[86:87], 10, v[86:87]
	v_lshl_add_u64 v[86:87], v[122:123], 0, v[86:87]
	global_load_dwordx2 v[134:135], v[84:85], off
	global_load_dwordx2 v[136:137], v[86:87], off
	s_andn2_b64 vcc, exec, s[0:1]
	s_mov_b64 s[0:1], -1
	s_nop 1
	v_add_f32_dpp v250, v250, v250 row_shr:1 row_mask:0xf bank_mask:0xf
	s_nop 1
	v_add_f32_dpp v250, v250, v250 row_shr:2 row_mask:0xf bank_mask:0xf
	s_nop 1
	v_add_f32_dpp v250, v250, v250 row_shr:4 row_mask:0xf bank_mask:0xf
	s_nop 1
	v_add_f32_dpp v250, v250, v250 row_shr:8 row_mask:0xf bank_mask:0xf
	s_nop 1
	v_add_f32_dpp v250, v250, v250 row_bcast:15 row_mask:0xa bank_mask:0xf
	s_nop 1
	v_add_f32_dpp v250, v250, v250 row_bcast:31 row_mask:0xc bank_mask:0xf
	v_mov_b32_e32 v84, v250
	v_sub_f32_e32 v85, v92, v84
	v_mov_b32_e32 v251, v85
	s_nop 1
	v_max_f32_dpp v251, v251, v251 row_shr:1 row_mask:0xf bank_mask:0xf
	s_nop 1
	v_max_f32_dpp v251, v251, v251 row_shr:2 row_mask:0xf bank_mask:0xf
	s_nop 1
	v_max_f32_dpp v251, v251, v251 row_shr:4 row_mask:0xf bank_mask:0xf
	s_nop 1
	v_max_f32_dpp v251, v251, v251 row_shr:8 row_mask:0xf bank_mask:0xf
	s_nop 1
	v_max_f32_dpp v251, v251, v251 row_bcast:15 row_mask:0xa bank_mask:0xf
	s_nop 1
	v_max_f32_dpp v251, v251, v251 row_bcast:31 row_mask:0xc bank_mask:0xf
	v_max_f32_e64 v87, s28, s28
	v_max_f32_e32 v86, v87, v251
	v_lshl_or_b32 v87, v211, 2, v226
	ds_bpermute_b32 v88, v87, v86
	v_add_f32_e32 v84, v84, v86
	v_sub_f32_e32 v89, s28, v86
	v_mul_f32_e32 v89, 0x3fb8aa3b, v89
	v_mul_f32_e32 v90, 0xbfb8aa3b, v84
	s_waitcnt lgkmcnt(0)
	v_sub_f32_e32 v91, v85, v88
	v_exp_f32_e32 v89, v89
	v_exp_f32_e32 v90, v90
	v_mul_f32_e32 v91, 0x3fb8aa3b, v91
	v_sub_f32_e32 v88, s28, v88
	v_exp_f32_e32 v91, v91
	v_mul_f32_e32 v88, 0x3fb8aa3b, v88
	ds_bpermute_b32 v84, v87, v84
	v_exp_f32_e32 v88, v88
	ds_write2st64_b32 v174, v86, v85 offset1:1
	ds_write2st64_b32 v174, v89, v90 offset0:2 offset1:3
	ds_write_b32 v174, v91 offset:1024
	s_waitcnt lgkmcnt(0)
	s_barrier
	v_readfirstlane_b32 s18, v88
	s_waitcnt lgkmcnt(0)
	v_readfirstlane_b32 s28, v84
	s_cbranch_vccnz .LBB0_429
	v_xor_b32_e32 v144, 32, v211
	s_mov_b64 s[0:1], 0
